# mod and bias projections: weight rows streamed through a scalar row pointer, 16 rows per step issued one step ahead (was 4 or 8 loads per memory round trip)
# speedup vs baseline: 1.0108x; 1.0108x over previous
; __device__ __forceinline__ void bias_phase(const Params& p, char* smem, int tid, int bid) {
;     ...
;     const int cl = tid & 127, kg = tid >> 7, col = chunk * 128 + cl;
;     const bool valid = col < ncols;
;     const float* Wc = W + (valid ? col : 0);
;     float acc[9];
; #pragma unroll
;     for (int r = 0; r < 9; ++r) acc[r] = 0.f;
; #pragma unroll 8
;     for (int k = kg * 256; k < kg * 256 + 256; ++k) {
;       const float w = Wc[(size_t)k * ld];
; #pragma unroll
;       for (int r = 0; r < 9; ++r) acc[r] = fmaf(sL[r * 1024 + k], w, acc[r]);
;     }
.LBB0_834:
	s_or_b64 exec, exec, s[0:1]
	s_lshl_b32 s0, s31, 7
	v_or_b32_e32 v0, s0, v39
	v_cmp_gt_i32_e32 vcc, s16, v0
	v_mov_b32_e32 v30, 0
	s_mov_b32 s1, 0
	v_cndmask_b32_e32 v0, 0, v0, vcc
	v_ashrrev_i32_e32 v1, 31, v0
	v_lshlrev_b64 v[0:1], 2, v[0:1]
	v_mad_u64_u32 v[0:1], s[18:19], v26, s16, v[0:1]
	v_mov_b32_e32 v2, v1
	v_mad_u64_u32 v[2:3], s[18:19], v27, s16, v[2:3]
	v_mov_b32_e32 v1, v2
	v_mov_b32_e32 v184, v0
	v_lshl_add_u64 v[28:29], s[22:23], 0, v[0:1]
	s_mov_b64 s[18:19], s[22:23]
	s_lshl_b64 s[20:21], s[16:17], 2
	v_mov_b32_e32 v31, v30
	v_mov_b32_e32 v32, v30
	v_mov_b32_e32 v33, v30
	v_mov_b32_e32 v34, v30
	v_mov_b32_e32 v35, v30
	v_mov_b32_e32 v36, v30
	v_mov_b32_e32 v37, v30
	v_mov_b32_e32 v48, v30
	s_waitcnt lgkmcnt(0)
	s_barrier
	global_load_dword v120, v184, s[18:19]
	s_add_u32 s18, s18, s20
	s_addc_u32 s19, s19, 0
	global_load_dword v122, v184, s[18:19]
	s_add_u32 s18, s18, s20
	s_addc_u32 s19, s19, 0
	global_load_dword v124, v184, s[18:19]
	s_add_u32 s18, s18, s20
	s_addc_u32 s19, s19, 0
	global_load_dword v126, v184, s[18:19]
	s_add_u32 s18, s18, s20
	s_addc_u32 s19, s19, 0
	global_load_dword v128, v184, s[18:19]
	s_add_u32 s18, s18, s20
	s_addc_u32 s19, s19, 0
	global_load_dword v130, v184, s[18:19]
	s_add_u32 s18, s18, s20
	s_addc_u32 s19, s19, 0
	global_load_dword v132, v184, s[18:19]
	s_add_u32 s18, s18, s20
	s_addc_u32 s19, s19, 0
	global_load_dword v134, v184, s[18:19]
	s_add_u32 s18, s18, s20
	s_addc_u32 s19, s19, 0
	global_load_dword v136, v184, s[18:19]
	s_add_u32 s18, s18, s20
	s_addc_u32 s19, s19, 0
	global_load_dword v138, v184, s[18:19]
	s_add_u32 s18, s18, s20
	s_addc_u32 s19, s19, 0
	global_load_dword v140, v184, s[18:19]
	s_add_u32 s18, s18, s20
	s_addc_u32 s19, s19, 0
	global_load_dword v142, v184, s[18:19]
	s_add_u32 s18, s18, s20
	s_addc_u32 s19, s19, 0
	global_load_dword v144, v184, s[18:19]
	s_add_u32 s18, s18, s20
	s_addc_u32 s19, s19, 0
	global_load_dword v146, v184, s[18:19]
	s_add_u32 s18, s18, s20
	s_addc_u32 s19, s19, 0
	global_load_dword v148, v184, s[18:19]
	s_add_u32 s18, s18, s20
	s_addc_u32 s19, s19, 0
	global_load_dword v150, v184, s[18:19]
	s_add_u32 s18, s18, s20
	s_addc_u32 s19, s19, 0
.LBB0_835:
	global_load_dword v152, v184, s[18:19]
	s_add_u32 s18, s18, s20
	s_addc_u32 s19, s19, 0
	global_load_dword v154, v184, s[18:19]
	s_add_u32 s18, s18, s20
	s_addc_u32 s19, s19, 0
	global_load_dword v156, v184, s[18:19]
	s_add_u32 s18, s18, s20
	s_addc_u32 s19, s19, 0
	global_load_dword v158, v184, s[18:19]
	s_add_u32 s18, s18, s20
	s_addc_u32 s19, s19, 0
	global_load_dword v160, v184, s[18:19]
	s_add_u32 s18, s18, s20
	s_addc_u32 s19, s19, 0
	global_load_dword v162, v184, s[18:19]
	s_add_u32 s18, s18, s20
	s_addc_u32 s19, s19, 0
	global_load_dword v164, v184, s[18:19]
	s_add_u32 s18, s18, s20
	s_addc_u32 s19, s19, 0
	global_load_dword v166, v184, s[18:19]
	s_add_u32 s18, s18, s20
	s_addc_u32 s19, s19, 0
	global_load_dword v168, v184, s[18:19]
	s_add_u32 s18, s18, s20
	s_addc_u32 s19, s19, 0
	global_load_dword v170, v184, s[18:19]
	s_add_u32 s18, s18, s20
	s_addc_u32 s19, s19, 0
	global_load_dword v172, v184, s[18:19]
	s_add_u32 s18, s18, s20
	s_addc_u32 s19, s19, 0
	global_load_dword v174, v184, s[18:19]
	s_add_u32 s18, s18, s20
	s_addc_u32 s19, s19, 0
	global_load_dword v176, v184, s[18:19]
	s_add_u32 s18, s18, s20
	s_addc_u32 s19, s19, 0
	global_load_dword v178, v184, s[18:19]
	s_add_u32 s18, s18, s20
	s_addc_u32 s19, s19, 0
	global_load_dword v180, v184, s[18:19]
	s_add_u32 s18, s18, s20
	s_addc_u32 s19, s19, 0
	global_load_dword v182, v184, s[18:19]
	s_add_u32 s18, s18, s20
	s_addc_u32 s19, s19, 0
	v_add_u32_e32 v16, s1, v45
	ds_read_b128 v[50:53], v16
	ds_read_b128 v[54:57], v16 offset:16
	ds_read_b128 v[20:23], v16 offset:4096
	ds_read_b128 v[0:3], v16 offset:4112
	ds_read_b128 v[58:61], v16 offset:8192
	ds_read_b128 v[62:65], v16 offset:8208
	ds_read_b128 v[66:69], v16 offset:12288
	ds_read_b128 v[4:7], v16 offset:12304
	ds_read_b128 v[70:73], v16 offset:16384
	ds_read_b128 v[74:77], v16 offset:16400
	ds_read_b128 v[78:81], v16 offset:20480
	ds_read_b128 v[8:11], v16 offset:20496
	ds_read_b128 v[82:85], v16 offset:24576
	ds_read_b128 v[86:89], v16 offset:24592
	ds_read_b128 v[90:93], v16 offset:28672
	ds_read_b128 v[12:15], v16 offset:28688
	ds_read_b128 v[94:97], v16 offset:32768
	ds_read_b128 v[16:19], v16 offset:32784
	s_waitcnt lgkmcnt(14)
	v_mov_b32_e32 v110, v50
	s_waitcnt lgkmcnt(13)
	v_mov_b32_e32 v112, v58
	v_mov_b32_e32 v111, v20
	s_waitcnt lgkmcnt(11)
	v_mov_b32_e32 v113, v66
	s_waitcnt lgkmcnt(9)
	v_mov_b32_e32 v114, v70
	s_waitcnt lgkmcnt(7)
	v_mov_b32_e32 v115, v78
	s_waitcnt lgkmcnt(5)
	v_mov_b32_e32 v116, v82
	s_waitcnt lgkmcnt(3)
	v_mov_b32_e32 v117, v90
	v_mov_b32_e32 v20, v51
	v_mov_b32_e32 v66, v59
	v_mov_b32_e32 v78, v71
	v_mov_b32_e32 v90, v83
	v_mov_b32_e32 v70, v52
	v_mov_b32_e32 v71, v22
	v_mov_b32_e32 v82, v60
	v_mov_b32_e32 v83, v68
	v_mov_b32_e32 v100, v72
	v_mov_b32_e32 v101, v80
	v_mov_b32_e32 v118, v84
	v_mov_b32_e32 v119, v92
	v_mov_b32_e32 v22, v53
	v_mov_b32_e32 v68, v61
	v_mov_b32_e32 v80, v73
	v_mov_b32_e32 v92, v85
	v_mov_b32_e32 v52, v54
	v_mov_b32_e32 v53, v0
	v_mov_b32_e32 v60, v62
	v_mov_b32_e32 v61, v4
	v_mov_b32_e32 v72, v74
	v_mov_b32_e32 v73, v8
	v_mov_b32_e32 v84, v86
	s_waitcnt lgkmcnt(2)
	v_mov_b32_e32 v85, v12
	v_mov_b32_e32 v0, v55
	v_mov_b32_e32 v4, v63
	v_mov_b32_e32 v8, v75
	v_mov_b32_e32 v12, v87
	v_mov_b32_e32 v54, v56
	v_mov_b32_e32 v55, v2
	v_mov_b32_e32 v62, v64
	v_mov_b32_e32 v63, v6
	v_mov_b32_e32 v74, v76
	v_mov_b32_e32 v75, v10
	v_mov_b32_e32 v86, v88
	v_mov_b32_e32 v87, v14
	s_add_i32 s1, s1, 32
	v_mov_b32_e32 v2, v57
	v_mov_b32_e32 v6, v65
	v_mov_b32_e32 v10, v77
	v_mov_b32_e32 v14, v89
	s_waitcnt vmcnt(31)
; __device__ __forceinline__ void bias_phase(const Params& p, char* smem, int tid, int bid) {
;     ...
; #pragma unroll 8
;     for (int k = kg * 256; k < kg * 256 + 256; ++k) {
;       const float w = Wc[(size_t)k * ld];
; #pragma unroll
;       for (int r = 0; r < 9; ++r) acc[r] = fmaf(sL[r * 1024 + k], w, acc[r]);
;     }
	v_pk_fma_f32 v[30:31], v[110:111], v[120:121], v[30:31] op_sel_hi:[1,0,1]
	v_pk_fma_f32 v[32:33], v[112:113], v[120:121], v[32:33] op_sel_hi:[1,0,1]
	v_pk_fma_f32 v[34:35], v[114:115], v[120:121], v[34:35] op_sel_hi:[1,0,1]
	v_pk_fma_f32 v[36:37], v[116:117], v[120:121], v[36:37] op_sel_hi:[1,0,1]
	s_waitcnt lgkmcnt(1)
	v_fmac_f32_e32 v48, v94, v120
	s_waitcnt vmcnt(30)
	v_pk_fma_f32 v[20:21], v[20:21], v[122:123], v[30:31] op_sel_hi:[1,0,1]
	v_pk_fma_f32 v[30:31], v[66:67], v[122:123], v[32:33] op_sel_hi:[1,0,1]
	v_pk_fma_f32 v[32:33], v[78:79], v[122:123], v[34:35] op_sel_hi:[1,0,1]
	v_pk_fma_f32 v[34:35], v[90:91], v[122:123], v[36:37] op_sel_hi:[1,0,1]
	v_fmac_f32_e32 v48, v95, v122
	s_waitcnt vmcnt(29)
	v_pk_fma_f32 v[20:21], v[70:71], v[124:125], v[20:21] op_sel_hi:[1,0,1]
	v_pk_fma_f32 v[30:31], v[82:83], v[124:125], v[30:31] op_sel_hi:[1,0,1]
	v_pk_fma_f32 v[32:33], v[100:101], v[124:125], v[32:33] op_sel_hi:[1,0,1]
	v_pk_fma_f32 v[34:35], v[118:119], v[124:125], v[34:35] op_sel_hi:[1,0,1]
	v_fmac_f32_e32 v48, v96, v124
	s_waitcnt vmcnt(28)
	v_pk_fma_f32 v[20:21], v[22:23], v[126:127], v[20:21] op_sel_hi:[1,0,1]
	v_pk_fma_f32 v[22:23], v[68:69], v[126:127], v[30:31] op_sel_hi:[1,0,1]
	v_pk_fma_f32 v[30:31], v[80:81], v[126:127], v[32:33] op_sel_hi:[1,0,1]
	v_pk_fma_f32 v[32:33], v[92:93], v[126:127], v[34:35] op_sel_hi:[1,0,1]
	v_fmac_f32_e32 v48, v97, v126
	s_waitcnt vmcnt(27)
	v_pk_fma_f32 v[20:21], v[52:53], v[128:129], v[20:21] op_sel_hi:[1,0,1]
	v_pk_fma_f32 v[22:23], v[60:61], v[128:129], v[22:23] op_sel_hi:[1,0,1]
	v_pk_fma_f32 v[30:31], v[72:73], v[128:129], v[30:31] op_sel_hi:[1,0,1]
	v_pk_fma_f32 v[32:33], v[84:85], v[128:129], v[32:33] op_sel_hi:[1,0,1]
	s_waitcnt lgkmcnt(0)
	v_fmac_f32_e32 v48, v16, v128
	s_waitcnt vmcnt(26)
	v_pk_fma_f32 v[0:1], v[0:1], v[130:131], v[20:21] op_sel_hi:[1,0,1]
	v_pk_fma_f32 v[4:5], v[4:5], v[130:131], v[22:23] op_sel_hi:[1,0,1]
	v_pk_fma_f32 v[8:9], v[8:9], v[130:131], v[30:31] op_sel_hi:[1,0,1]
	v_pk_fma_f32 v[12:13], v[12:13], v[130:131], v[32:33] op_sel_hi:[1,0,1]
	v_fmac_f32_e32 v48, v17, v130
	s_waitcnt vmcnt(25)
	v_pk_fma_f32 v[0:1], v[54:55], v[132:133], v[0:1] op_sel_hi:[1,0,1]
	v_pk_fma_f32 v[4:5], v[62:63], v[132:133], v[4:5] op_sel_hi:[1,0,1]
	v_pk_fma_f32 v[8:9], v[74:75], v[132:133], v[8:9] op_sel_hi:[1,0,1]
	v_pk_fma_f32 v[12:13], v[86:87], v[132:133], v[12:13] op_sel_hi:[1,0,1]
	v_fmac_f32_e32 v48, v18, v132
	s_waitcnt vmcnt(24)
	v_pk_fma_f32 v[30:31], v[2:3], v[134:135], v[0:1] op_sel_hi:[1,0,1]
	v_pk_fma_f32 v[32:33], v[6:7], v[134:135], v[4:5] op_sel_hi:[1,0,1]
	v_pk_fma_f32 v[34:35], v[10:11], v[134:135], v[8:9] op_sel_hi:[1,0,1]
	v_pk_fma_f32 v[36:37], v[14:15], v[134:135], v[12:13] op_sel_hi:[1,0,1]
	v_fmac_f32_e32 v48, v19, v134
	v_add_u32_e32 v16, s1, v45
	ds_read_b128 v[50:53], v16
	ds_read_b128 v[54:57], v16 offset:16
	ds_read_b128 v[20:23], v16 offset:4096
	ds_read_b128 v[0:3], v16 offset:4112
	ds_read_b128 v[58:61], v16 offset:8192
	ds_read_b128 v[62:65], v16 offset:8208
	ds_read_b128 v[66:69], v16 offset:12288
	ds_read_b128 v[4:7], v16 offset:12304
	ds_read_b128 v[70:73], v16 offset:16384
	ds_read_b128 v[74:77], v16 offset:16400
	ds_read_b128 v[78:81], v16 offset:20480
	ds_read_b128 v[8:11], v16 offset:20496
	ds_read_b128 v[82:85], v16 offset:24576
	ds_read_b128 v[86:89], v16 offset:24592
	ds_read_b128 v[90:93], v16 offset:28672
	ds_read_b128 v[12:15], v16 offset:28688
	ds_read_b128 v[94:97], v16 offset:32768
	ds_read_b128 v[16:19], v16 offset:32784
	s_waitcnt lgkmcnt(14)
	v_mov_b32_e32 v110, v50
	s_waitcnt lgkmcnt(13)
	v_mov_b32_e32 v112, v58
	v_mov_b32_e32 v111, v20
	s_waitcnt lgkmcnt(11)
	v_mov_b32_e32 v113, v66
	s_waitcnt lgkmcnt(9)
	v_mov_b32_e32 v114, v70
	s_waitcnt lgkmcnt(7)
	v_mov_b32_e32 v115, v78
	s_waitcnt lgkmcnt(5)
	v_mov_b32_e32 v116, v82
	s_waitcnt lgkmcnt(3)
	v_mov_b32_e32 v117, v90
	v_mov_b32_e32 v20, v51
	v_mov_b32_e32 v66, v59
	v_mov_b32_e32 v78, v71
	v_mov_b32_e32 v90, v83
	v_mov_b32_e32 v70, v52
	v_mov_b32_e32 v71, v22
	v_mov_b32_e32 v82, v60
	v_mov_b32_e32 v83, v68
	v_mov_b32_e32 v100, v72
	v_mov_b32_e32 v101, v80
	v_mov_b32_e32 v118, v84
	v_mov_b32_e32 v119, v92
	v_mov_b32_e32 v22, v53
	v_mov_b32_e32 v68, v61
	v_mov_b32_e32 v80, v73
	v_mov_b32_e32 v92, v85
	v_mov_b32_e32 v52, v54
	v_mov_b32_e32 v53, v0
	v_mov_b32_e32 v60, v62
	v_mov_b32_e32 v61, v4
	v_mov_b32_e32 v72, v74
	v_mov_b32_e32 v73, v8
	v_mov_b32_e32 v84, v86
	s_waitcnt lgkmcnt(2)
	v_mov_b32_e32 v85, v12
	v_mov_b32_e32 v0, v55
	v_mov_b32_e32 v4, v63
	v_mov_b32_e32 v8, v75
	v_mov_b32_e32 v12, v87
	v_mov_b32_e32 v54, v56
	v_mov_b32_e32 v55, v2
	v_mov_b32_e32 v62, v64
	v_mov_b32_e32 v63, v6
	v_mov_b32_e32 v74, v76
	v_mov_b32_e32 v75, v10
	v_mov_b32_e32 v86, v88
	v_mov_b32_e32 v87, v14
	s_add_i32 s1, s1, 32
	v_mov_b32_e32 v2, v57
	v_mov_b32_e32 v6, v65
	v_mov_b32_e32 v10, v77
	v_mov_b32_e32 v14, v89
	s_waitcnt vmcnt(23)
	v_pk_fma_f32 v[30:31], v[110:111], v[136:137], v[30:31] op_sel_hi:[1,0,1]
	v_pk_fma_f32 v[32:33], v[112:113], v[136:137], v[32:33] op_sel_hi:[1,0,1]
	v_pk_fma_f32 v[34:35], v[114:115], v[136:137], v[34:35] op_sel_hi:[1,0,1]
	v_pk_fma_f32 v[36:37], v[116:117], v[136:137], v[36:37] op_sel_hi:[1,0,1]
	s_waitcnt lgkmcnt(1)
	v_fmac_f32_e32 v48, v94, v136
	s_waitcnt vmcnt(22)
	v_pk_fma_f32 v[20:21], v[20:21], v[138:139], v[30:31] op_sel_hi:[1,0,1]
	v_pk_fma_f32 v[30:31], v[66:67], v[138:139], v[32:33] op_sel_hi:[1,0,1]
	v_pk_fma_f32 v[32:33], v[78:79], v[138:139], v[34:35] op_sel_hi:[1,0,1]
	v_pk_fma_f32 v[34:35], v[90:91], v[138:139], v[36:37] op_sel_hi:[1,0,1]
	v_fmac_f32_e32 v48, v95, v138
	s_waitcnt vmcnt(21)
; __device__ __forceinline__ void bias_phase(const Params& p, char* smem, int tid, int bid) {
;     ...
; #pragma unroll 8
;     for (int k = kg * 256; k < kg * 256 + 256; ++k) {
;       const float w = Wc[(size_t)k * ld];
; #pragma unroll
;       for (int r = 0; r < 9; ++r) acc[r] = fmaf(sL[r * 1024 + k], w, acc[r]);
;     }
	v_pk_fma_f32 v[20:21], v[70:71], v[140:141], v[20:21] op_sel_hi:[1,0,1]
	v_pk_fma_f32 v[30:31], v[82:83], v[140:141], v[30:31] op_sel_hi:[1,0,1]
	v_pk_fma_f32 v[32:33], v[100:101], v[140:141], v[32:33] op_sel_hi:[1,0,1]
	v_pk_fma_f32 v[34:35], v[118:119], v[140:141], v[34:35] op_sel_hi:[1,0,1]
	v_fmac_f32_e32 v48, v96, v140
	s_waitcnt vmcnt(20)
	v_pk_fma_f32 v[20:21], v[22:23], v[142:143], v[20:21] op_sel_hi:[1,0,1]
	v_pk_fma_f32 v[22:23], v[68:69], v[142:143], v[30:31] op_sel_hi:[1,0,1]
	v_pk_fma_f32 v[30:31], v[80:81], v[142:143], v[32:33] op_sel_hi:[1,0,1]
	v_pk_fma_f32 v[32:33], v[92:93], v[142:143], v[34:35] op_sel_hi:[1,0,1]
	v_fmac_f32_e32 v48, v97, v142
	s_waitcnt vmcnt(19)
	v_pk_fma_f32 v[20:21], v[52:53], v[144:145], v[20:21] op_sel_hi:[1,0,1]
	v_pk_fma_f32 v[22:23], v[60:61], v[144:145], v[22:23] op_sel_hi:[1,0,1]
	v_pk_fma_f32 v[30:31], v[72:73], v[144:145], v[30:31] op_sel_hi:[1,0,1]
	v_pk_fma_f32 v[32:33], v[84:85], v[144:145], v[32:33] op_sel_hi:[1,0,1]
	s_waitcnt lgkmcnt(0)
	v_fmac_f32_e32 v48, v16, v144
	s_waitcnt vmcnt(18)
	v_pk_fma_f32 v[0:1], v[0:1], v[146:147], v[20:21] op_sel_hi:[1,0,1]
	v_pk_fma_f32 v[4:5], v[4:5], v[146:147], v[22:23] op_sel_hi:[1,0,1]
	v_pk_fma_f32 v[8:9], v[8:9], v[146:147], v[30:31] op_sel_hi:[1,0,1]
	v_pk_fma_f32 v[12:13], v[12:13], v[146:147], v[32:33] op_sel_hi:[1,0,1]
	v_fmac_f32_e32 v48, v17, v146
	s_waitcnt vmcnt(17)
	v_pk_fma_f32 v[0:1], v[54:55], v[148:149], v[0:1] op_sel_hi:[1,0,1]
	v_pk_fma_f32 v[4:5], v[62:63], v[148:149], v[4:5] op_sel_hi:[1,0,1]
	v_pk_fma_f32 v[8:9], v[74:75], v[148:149], v[8:9] op_sel_hi:[1,0,1]
	v_pk_fma_f32 v[12:13], v[86:87], v[148:149], v[12:13] op_sel_hi:[1,0,1]
	v_fmac_f32_e32 v48, v18, v148
	s_waitcnt vmcnt(16)
	v_pk_fma_f32 v[30:31], v[2:3], v[150:151], v[0:1] op_sel_hi:[1,0,1]
	v_pk_fma_f32 v[32:33], v[6:7], v[150:151], v[4:5] op_sel_hi:[1,0,1]
	v_pk_fma_f32 v[34:35], v[10:11], v[150:151], v[8:9] op_sel_hi:[1,0,1]
	v_pk_fma_f32 v[36:37], v[14:15], v[150:151], v[12:13] op_sel_hi:[1,0,1]
	v_fmac_f32_e32 v48, v19, v150
	s_lshl_b32 s21, s20, 4
	s_cmpk_eq_i32 s1, 0x3c0
	s_cselect_b32 s21, s21, 0
	s_sub_u32 s18, s18, s21
	s_subb_u32 s19, s19, 0
	global_load_dword v120, v184, s[18:19]
	s_add_u32 s18, s18, s20
	s_addc_u32 s19, s19, 0
	global_load_dword v122, v184, s[18:19]
	s_add_u32 s18, s18, s20
	s_addc_u32 s19, s19, 0
	global_load_dword v124, v184, s[18:19]
	s_add_u32 s18, s18, s20
	s_addc_u32 s19, s19, 0
	global_load_dword v126, v184, s[18:19]
	s_add_u32 s18, s18, s20
	s_addc_u32 s19, s19, 0
	global_load_dword v128, v184, s[18:19]
	s_add_u32 s18, s18, s20
	s_addc_u32 s19, s19, 0
	global_load_dword v130, v184, s[18:19]
	s_add_u32 s18, s18, s20
	s_addc_u32 s19, s19, 0
	global_load_dword v132, v184, s[18:19]
	s_add_u32 s18, s18, s20
	s_addc_u32 s19, s19, 0
	global_load_dword v134, v184, s[18:19]
	s_add_u32 s18, s18, s20
	s_addc_u32 s19, s19, 0
	global_load_dword v136, v184, s[18:19]
	s_add_u32 s18, s18, s20
	s_addc_u32 s19, s19, 0
	global_load_dword v138, v184, s[18:19]
	s_add_u32 s18, s18, s20
	s_addc_u32 s19, s19, 0
	global_load_dword v140, v184, s[18:19]
	s_add_u32 s18, s18, s20
	s_addc_u32 s19, s19, 0
	global_load_dword v142, v184, s[18:19]
	s_add_u32 s18, s18, s20
	s_addc_u32 s19, s19, 0
	global_load_dword v144, v184, s[18:19]
	s_add_u32 s18, s18, s20
	s_addc_u32 s19, s19, 0
	global_load_dword v146, v184, s[18:19]
	s_add_u32 s18, s18, s20
	s_addc_u32 s19, s19, 0
	global_load_dword v148, v184, s[18:19]
	s_add_u32 s18, s18, s20
	s_addc_u32 s19, s19, 0
	global_load_dword v150, v184, s[18:19]
	s_add_u32 s18, s18, s20
	s_addc_u32 s19, s19, 0
	v_add_u32_e32 v16, s1, v45
	ds_read_b128 v[50:53], v16
	ds_read_b128 v[54:57], v16 offset:16
	ds_read_b128 v[20:23], v16 offset:4096
	ds_read_b128 v[0:3], v16 offset:4112
	ds_read_b128 v[58:61], v16 offset:8192
	ds_read_b128 v[62:65], v16 offset:8208
	ds_read_b128 v[66:69], v16 offset:12288
	ds_read_b128 v[4:7], v16 offset:12304
	ds_read_b128 v[70:73], v16 offset:16384
	ds_read_b128 v[74:77], v16 offset:16400
	ds_read_b128 v[78:81], v16 offset:20480
	ds_read_b128 v[8:11], v16 offset:20496
	ds_read_b128 v[82:85], v16 offset:24576
	ds_read_b128 v[86:89], v16 offset:24592
	ds_read_b128 v[90:93], v16 offset:28672
	ds_read_b128 v[12:15], v16 offset:28688
	ds_read_b128 v[94:97], v16 offset:32768
	ds_read_b128 v[16:19], v16 offset:32784
	s_waitcnt lgkmcnt(14)
	v_mov_b32_e32 v110, v50
	s_waitcnt lgkmcnt(13)
	v_mov_b32_e32 v112, v58
	v_mov_b32_e32 v111, v20
	s_waitcnt lgkmcnt(11)
	v_mov_b32_e32 v113, v66
	s_waitcnt lgkmcnt(9)
	v_mov_b32_e32 v114, v70
	s_waitcnt lgkmcnt(7)
	v_mov_b32_e32 v115, v78
	s_waitcnt lgkmcnt(5)
	v_mov_b32_e32 v116, v82
	s_waitcnt lgkmcnt(3)
	v_mov_b32_e32 v117, v90
	v_mov_b32_e32 v20, v51
	v_mov_b32_e32 v66, v59
	v_mov_b32_e32 v78, v71
	v_mov_b32_e32 v90, v83
	v_mov_b32_e32 v70, v52
	v_mov_b32_e32 v71, v22
	v_mov_b32_e32 v82, v60
	v_mov_b32_e32 v83, v68
	v_mov_b32_e32 v100, v72
	v_mov_b32_e32 v101, v80
	v_mov_b32_e32 v118, v84
	v_mov_b32_e32 v119, v92
	v_mov_b32_e32 v22, v53
	v_mov_b32_e32 v68, v61
	v_mov_b32_e32 v80, v73
	v_mov_b32_e32 v92, v85
	v_mov_b32_e32 v52, v54
	v_mov_b32_e32 v53, v0
	v_mov_b32_e32 v60, v62
	v_mov_b32_e32 v61, v4
	v_mov_b32_e32 v72, v74
	v_mov_b32_e32 v73, v8
	v_mov_b32_e32 v84, v86
	s_waitcnt lgkmcnt(2)
	v_mov_b32_e32 v85, v12
	v_mov_b32_e32 v0, v55
	v_mov_b32_e32 v4, v63
	v_mov_b32_e32 v8, v75
	v_mov_b32_e32 v12, v87
	v_mov_b32_e32 v54, v56
	v_mov_b32_e32 v55, v2
	v_mov_b32_e32 v62, v64
	v_mov_b32_e32 v63, v6
	v_mov_b32_e32 v74, v76
	v_mov_b32_e32 v75, v10
	v_mov_b32_e32 v86, v88
	v_mov_b32_e32 v87, v14
	s_add_i32 s1, s1, 32
	v_mov_b32_e32 v2, v57
	v_mov_b32_e32 v6, v65
	v_mov_b32_e32 v10, v77
	v_mov_b32_e32 v14, v89
	s_waitcnt vmcnt(31)
; __device__ __forceinline__ void bias_phase(const Params& p, char* smem, int tid, int bid) {
;     ...
; #pragma unroll 8
;     for (int k = kg * 256; k < kg * 256 + 256; ++k) {
;       const float w = Wc[(size_t)k * ld];
; #pragma unroll
;       for (int r = 0; r < 9; ++r) acc[r] = fmaf(sL[r * 1024 + k], w, acc[r]);
;     }
	v_pk_fma_f32 v[30:31], v[110:111], v[152:153], v[30:31] op_sel_hi:[1,0,1]
	v_pk_fma_f32 v[32:33], v[112:113], v[152:153], v[32:33] op_sel_hi:[1,0,1]
	v_pk_fma_f32 v[34:35], v[114:115], v[152:153], v[34:35] op_sel_hi:[1,0,1]
	v_pk_fma_f32 v[36:37], v[116:117], v[152:153], v[36:37] op_sel_hi:[1,0,1]
	s_waitcnt lgkmcnt(1)
	v_fmac_f32_e32 v48, v94, v152
	s_waitcnt vmcnt(30)
	v_pk_fma_f32 v[20:21], v[20:21], v[154:155], v[30:31] op_sel_hi:[1,0,1]
	v_pk_fma_f32 v[30:31], v[66:67], v[154:155], v[32:33] op_sel_hi:[1,0,1]
	v_pk_fma_f32 v[32:33], v[78:79], v[154:155], v[34:35] op_sel_hi:[1,0,1]
	v_pk_fma_f32 v[34:35], v[90:91], v[154:155], v[36:37] op_sel_hi:[1,0,1]
	v_fmac_f32_e32 v48, v95, v154
	s_waitcnt vmcnt(29)
	v_pk_fma_f32 v[20:21], v[70:71], v[156:157], v[20:21] op_sel_hi:[1,0,1]
	v_pk_fma_f32 v[30:31], v[82:83], v[156:157], v[30:31] op_sel_hi:[1,0,1]
	v_pk_fma_f32 v[32:33], v[100:101], v[156:157], v[32:33] op_sel_hi:[1,0,1]
	v_pk_fma_f32 v[34:35], v[118:119], v[156:157], v[34:35] op_sel_hi:[1,0,1]
	v_fmac_f32_e32 v48, v96, v156
	s_waitcnt vmcnt(28)
	v_pk_fma_f32 v[20:21], v[22:23], v[158:159], v[20:21] op_sel_hi:[1,0,1]
	v_pk_fma_f32 v[22:23], v[68:69], v[158:159], v[30:31] op_sel_hi:[1,0,1]
	v_pk_fma_f32 v[30:31], v[80:81], v[158:159], v[32:33] op_sel_hi:[1,0,1]
	v_pk_fma_f32 v[32:33], v[92:93], v[158:159], v[34:35] op_sel_hi:[1,0,1]
	v_fmac_f32_e32 v48, v97, v158
	s_waitcnt vmcnt(27)
	v_pk_fma_f32 v[20:21], v[52:53], v[160:161], v[20:21] op_sel_hi:[1,0,1]
	v_pk_fma_f32 v[22:23], v[60:61], v[160:161], v[22:23] op_sel_hi:[1,0,1]
	v_pk_fma_f32 v[30:31], v[72:73], v[160:161], v[30:31] op_sel_hi:[1,0,1]
	v_pk_fma_f32 v[32:33], v[84:85], v[160:161], v[32:33] op_sel_hi:[1,0,1]
	s_waitcnt lgkmcnt(0)
	v_fmac_f32_e32 v48, v16, v160
	s_waitcnt vmcnt(26)
	v_pk_fma_f32 v[0:1], v[0:1], v[162:163], v[20:21] op_sel_hi:[1,0,1]
	v_pk_fma_f32 v[4:5], v[4:5], v[162:163], v[22:23] op_sel_hi:[1,0,1]
	v_pk_fma_f32 v[8:9], v[8:9], v[162:163], v[30:31] op_sel_hi:[1,0,1]
	v_pk_fma_f32 v[12:13], v[12:13], v[162:163], v[32:33] op_sel_hi:[1,0,1]
	v_fmac_f32_e32 v48, v17, v162
	s_waitcnt vmcnt(25)
	v_pk_fma_f32 v[0:1], v[54:55], v[164:165], v[0:1] op_sel_hi:[1,0,1]
	v_pk_fma_f32 v[4:5], v[62:63], v[164:165], v[4:5] op_sel_hi:[1,0,1]
	v_pk_fma_f32 v[8:9], v[74:75], v[164:165], v[8:9] op_sel_hi:[1,0,1]
	v_pk_fma_f32 v[12:13], v[86:87], v[164:165], v[12:13] op_sel_hi:[1,0,1]
	v_fmac_f32_e32 v48, v18, v164
	s_waitcnt vmcnt(24)
	v_pk_fma_f32 v[30:31], v[2:3], v[166:167], v[0:1] op_sel_hi:[1,0,1]
	v_pk_fma_f32 v[32:33], v[6:7], v[166:167], v[4:5] op_sel_hi:[1,0,1]
	v_pk_fma_f32 v[34:35], v[10:11], v[166:167], v[8:9] op_sel_hi:[1,0,1]
	v_pk_fma_f32 v[36:37], v[14:15], v[166:167], v[12:13] op_sel_hi:[1,0,1]
	v_fmac_f32_e32 v48, v19, v166
	v_add_u32_e32 v16, s1, v45
	ds_read_b128 v[50:53], v16
	ds_read_b128 v[54:57], v16 offset:16
	ds_read_b128 v[20:23], v16 offset:4096
	ds_read_b128 v[0:3], v16 offset:4112
	ds_read_b128 v[58:61], v16 offset:8192
	ds_read_b128 v[62:65], v16 offset:8208
	ds_read_b128 v[66:69], v16 offset:12288
	ds_read_b128 v[4:7], v16 offset:12304
	ds_read_b128 v[70:73], v16 offset:16384
	ds_read_b128 v[74:77], v16 offset:16400
	ds_read_b128 v[78:81], v16 offset:20480
	ds_read_b128 v[8:11], v16 offset:20496
	ds_read_b128 v[82:85], v16 offset:24576
	ds_read_b128 v[86:89], v16 offset:24592
	ds_read_b128 v[90:93], v16 offset:28672
	ds_read_b128 v[12:15], v16 offset:28688
	ds_read_b128 v[94:97], v16 offset:32768
	ds_read_b128 v[16:19], v16 offset:32784
	s_waitcnt lgkmcnt(14)
	v_mov_b32_e32 v110, v50
	s_waitcnt lgkmcnt(13)
	v_mov_b32_e32 v112, v58
	v_mov_b32_e32 v111, v20
	s_waitcnt lgkmcnt(11)
	v_mov_b32_e32 v113, v66
	s_waitcnt lgkmcnt(9)
	v_mov_b32_e32 v114, v70
	s_waitcnt lgkmcnt(7)
	v_mov_b32_e32 v115, v78
	s_waitcnt lgkmcnt(5)
	v_mov_b32_e32 v116, v82
	s_waitcnt lgkmcnt(3)
	v_mov_b32_e32 v117, v90
	v_mov_b32_e32 v20, v51
	v_mov_b32_e32 v66, v59
	v_mov_b32_e32 v78, v71
	v_mov_b32_e32 v90, v83
	v_mov_b32_e32 v70, v52
	v_mov_b32_e32 v71, v22
	v_mov_b32_e32 v82, v60
	v_mov_b32_e32 v83, v68
	v_mov_b32_e32 v100, v72
	v_mov_b32_e32 v101, v80
	v_mov_b32_e32 v118, v84
	v_mov_b32_e32 v119, v92
	v_mov_b32_e32 v22, v53
	v_mov_b32_e32 v68, v61
	v_mov_b32_e32 v80, v73
	v_mov_b32_e32 v92, v85
	v_mov_b32_e32 v52, v54
	v_mov_b32_e32 v53, v0
	v_mov_b32_e32 v60, v62
	v_mov_b32_e32 v61, v4
	v_mov_b32_e32 v72, v74
	v_mov_b32_e32 v73, v8
	v_mov_b32_e32 v84, v86
	s_waitcnt lgkmcnt(2)
; __device__ __forceinline__ void bias_phase(const Params& p, char* smem, int tid, int bid) {
;     ...
; #pragma unroll 8
;     for (int k = kg * 256; k < kg * 256 + 256; ++k) {
;       const float w = Wc[(size_t)k * ld];
; #pragma unroll
;       for (int r = 0; r < 9; ++r) acc[r] = fmaf(sL[r * 1024 + k], w, acc[r]);
;     }
; #pragma unroll
;     for (int r = 0; r < 9; ++r) red[(kg * 9 + r) * 128 + cl] = acc[r];
;     __syncthreads();
	v_mov_b32_e32 v85, v12
	v_mov_b32_e32 v0, v55
	v_mov_b32_e32 v4, v63
	v_mov_b32_e32 v8, v75
	v_mov_b32_e32 v12, v87
	v_mov_b32_e32 v54, v56
	v_mov_b32_e32 v55, v2
	v_mov_b32_e32 v62, v64
	v_mov_b32_e32 v63, v6
	v_mov_b32_e32 v74, v76
	v_mov_b32_e32 v75, v10
	v_mov_b32_e32 v86, v88
	v_mov_b32_e32 v87, v14
	s_add_i32 s1, s1, 32
	v_mov_b32_e32 v2, v57
	v_mov_b32_e32 v6, v65
	v_mov_b32_e32 v10, v77
	v_mov_b32_e32 v14, v89
	s_waitcnt vmcnt(23)
	v_pk_fma_f32 v[30:31], v[110:111], v[168:169], v[30:31] op_sel_hi:[1,0,1]
	v_pk_fma_f32 v[32:33], v[112:113], v[168:169], v[32:33] op_sel_hi:[1,0,1]
	v_pk_fma_f32 v[34:35], v[114:115], v[168:169], v[34:35] op_sel_hi:[1,0,1]
	v_pk_fma_f32 v[36:37], v[116:117], v[168:169], v[36:37] op_sel_hi:[1,0,1]
	s_waitcnt lgkmcnt(1)
	v_fmac_f32_e32 v48, v94, v168
	s_waitcnt vmcnt(22)
	v_pk_fma_f32 v[20:21], v[20:21], v[170:171], v[30:31] op_sel_hi:[1,0,1]
	v_pk_fma_f32 v[30:31], v[66:67], v[170:171], v[32:33] op_sel_hi:[1,0,1]
	v_pk_fma_f32 v[32:33], v[78:79], v[170:171], v[34:35] op_sel_hi:[1,0,1]
	v_pk_fma_f32 v[34:35], v[90:91], v[170:171], v[36:37] op_sel_hi:[1,0,1]
	v_fmac_f32_e32 v48, v95, v170
	s_waitcnt vmcnt(21)
	v_pk_fma_f32 v[20:21], v[70:71], v[172:173], v[20:21] op_sel_hi:[1,0,1]
	v_pk_fma_f32 v[30:31], v[82:83], v[172:173], v[30:31] op_sel_hi:[1,0,1]
	v_pk_fma_f32 v[32:33], v[100:101], v[172:173], v[32:33] op_sel_hi:[1,0,1]
	v_pk_fma_f32 v[34:35], v[118:119], v[172:173], v[34:35] op_sel_hi:[1,0,1]
	v_fmac_f32_e32 v48, v96, v172
	s_waitcnt vmcnt(20)
	v_pk_fma_f32 v[20:21], v[22:23], v[174:175], v[20:21] op_sel_hi:[1,0,1]
	v_pk_fma_f32 v[22:23], v[68:69], v[174:175], v[30:31] op_sel_hi:[1,0,1]
	v_pk_fma_f32 v[30:31], v[80:81], v[174:175], v[32:33] op_sel_hi:[1,0,1]
	v_pk_fma_f32 v[32:33], v[92:93], v[174:175], v[34:35] op_sel_hi:[1,0,1]
	v_fmac_f32_e32 v48, v97, v174
	s_waitcnt vmcnt(19)
	v_pk_fma_f32 v[20:21], v[52:53], v[176:177], v[20:21] op_sel_hi:[1,0,1]
	v_pk_fma_f32 v[22:23], v[60:61], v[176:177], v[22:23] op_sel_hi:[1,0,1]
	v_pk_fma_f32 v[30:31], v[72:73], v[176:177], v[30:31] op_sel_hi:[1,0,1]
	v_pk_fma_f32 v[32:33], v[84:85], v[176:177], v[32:33] op_sel_hi:[1,0,1]
	s_waitcnt lgkmcnt(0)
	v_fmac_f32_e32 v48, v16, v176
	s_waitcnt vmcnt(18)
	v_pk_fma_f32 v[0:1], v[0:1], v[178:179], v[20:21] op_sel_hi:[1,0,1]
	v_pk_fma_f32 v[4:5], v[4:5], v[178:179], v[22:23] op_sel_hi:[1,0,1]
	v_pk_fma_f32 v[8:9], v[8:9], v[178:179], v[30:31] op_sel_hi:[1,0,1]
	v_pk_fma_f32 v[12:13], v[12:13], v[178:179], v[32:33] op_sel_hi:[1,0,1]
	v_fmac_f32_e32 v48, v17, v178
	s_waitcnt vmcnt(17)
	v_pk_fma_f32 v[0:1], v[54:55], v[180:181], v[0:1] op_sel_hi:[1,0,1]
	v_pk_fma_f32 v[4:5], v[62:63], v[180:181], v[4:5] op_sel_hi:[1,0,1]
	v_pk_fma_f32 v[8:9], v[74:75], v[180:181], v[8:9] op_sel_hi:[1,0,1]
	v_pk_fma_f32 v[12:13], v[86:87], v[180:181], v[12:13] op_sel_hi:[1,0,1]
	v_fmac_f32_e32 v48, v18, v180
	s_waitcnt vmcnt(16)
	v_pk_fma_f32 v[30:31], v[2:3], v[182:183], v[0:1] op_sel_hi:[1,0,1]
	v_pk_fma_f32 v[32:33], v[6:7], v[182:183], v[4:5] op_sel_hi:[1,0,1]
	v_pk_fma_f32 v[34:35], v[10:11], v[182:183], v[8:9] op_sel_hi:[1,0,1]
	v_pk_fma_f32 v[36:37], v[14:15], v[182:183], v[12:13] op_sel_hi:[1,0,1]
	v_fmac_f32_e32 v48, v19, v182
	s_cmpk_eq_i32 s1, 0x400
	s_cbranch_scc0 .LBB0_835
	ds_write2st64_b32 v47, v30, v31 offset0:144 offset1:146
	ds_write2st64_b32 v47, v32, v33 offset0:148 offset1:150
	ds_write2st64_b32 v47, v34, v35 offset0:152 offset1:154
	ds_write2st64_b32 v47, v36, v37 offset0:156 offset1:158
	ds_write_b32 v47, v48 offset:40960
	s_waitcnt lgkmcnt(0)
	s_barrier
	s_and_saveexec_b64 s[18:19], s[6:7]
	s_cbranch_execz .LBB0_794
	s_lshl_b32 s1, s30, 1
	s_or_b32 s16, s1, s29
	s_ashr_i32 s1, s0, 31
	s_mul_i32 s16, s16, 9
	v_lshl_add_u64 v[0:1], s[0:1], 2, v[24:25]
	s_mov_b64 s[20:21], 0
	v_mov_b32_e32 v2, v46
	v_mov_b32_e32 v3, v208
	s_branch .LBB0_839

; __device__ __forceinline__ void mod_phase(const Params& p, char* smem, int tid, int bid) {
;     ...
;   for (int job = bid; job < 192; job += gridDim.x) {
;     const int l = job / 48, cch = job % 48, cl = tid & 127, kg = tid >> 7;
;     const float* W = p.in[6] + (size_t)l * 1024 * 6144 + cch * 128 + cl;
;     float acc[9];
.LBB0_852:
	s_or_b64 exec, exec, s[0:1]
	v_ashrrev_i32_e32 v7, 7, v208
	s_movk_i32 s4, 0x1200
	v_and_b32_e32 v0, 0x7f, v208
	v_mul_lo_u32 v8, v7, s4
	v_readlane_b32 s4, v253, 11
	v_lshlrev_b32_e32 v4, 8, v7
	v_lshlrev_b32_e32 v200, 2, v0
	v_readlane_b32 s5, v253, 12
	v_readlane_b32 s36, v254, 43
	s_waitcnt lgkmcnt(0)
	v_add_u32_e32 v1, 0, v200
	v_lshl_add_u64 v[2:3], s[4:5], 0, v[200:201]
	v_mad_i64_i32 v[4:5], s[4:5], v4, s63, 0
	s_movk_i32 s0, 0x480
	v_or_b32_e32 v4, v4, v200
	v_mov_b32_e32 v74, v4
	v_readlane_b32 s48, v254, 55
	v_readlane_b32 s49, v254, 56
	s_add_i32 s4, 0, 0x9000
	v_cmp_gt_i32_e64 s[0:1], s0, v208
	v_lshl_add_u64 v[4:5], s[48:49], 0, v[4:5]
	v_lshl_add_u32 v16, v7, 10, 0
	v_add_u32_e32 v17, s4, v6
	v_add_u32_e32 v18, v1, v8
	s_waitcnt vmcnt(0)
	s_barrier
	v_readlane_b32 s37, v254, 44
	v_readlane_b32 s38, v254, 45
	v_readlane_b32 s39, v254, 46
	v_readlane_b32 s40, v254, 47
	v_readlane_b32 s41, v254, 48
	v_readlane_b32 s42, v254, 49
	v_readlane_b32 s43, v254, 50
	v_readlane_b32 s44, v254, 51
	v_readlane_b32 s45, v254, 52
	v_readlane_b32 s46, v254, 53
	v_readlane_b32 s47, v254, 54
	v_readlane_b32 s50, v254, 57
	v_readlane_b32 s51, v254, 58
	s_branch .LBB0_854

; __device__ __forceinline__ void mod_phase(const Params& p, char* smem, int tid, int bid) {
;     ...
;     const int l = job / 48, cch = job % 48, cl = tid & 127, kg = tid >> 7;
;     const float* W = p.in[6] + (size_t)l * 1024 * 6144 + cch * 128 + cl;
;     float acc[9];
; #pragma unroll
;     for (int r = 0; r < 9; ++r) acc[r] = 0.f;
; #pragma unroll 4
;     for (int k = kg * 256; k < kg * 256 + 256; ++k) {
;       const float w = W[(size_t)k * 6144];
; #pragma unroll
;       for (int r = 0; r < 9; ++r) acc[r] = fmaf(sL[r * 1024 + k], w, acc[r]);
.LBB0_854:
	s_mul_hi_i32 s4, s62, 0x2aaaaaab
	s_lshr_b32 s5, s4, 31
	s_ashr_i32 s4, s4, 3
	s_add_i32 s4, s4, s5
	s_mul_i32 s5, s4, 48
	s_sub_i32 s10, s62, s5
	s_lshl_b32 s6, s10, 7
	s_ashr_i32 s7, s6, 31
	s_ashr_i32 s5, s4, 31
	s_mul_i32 s8, s4, 0x1800000
	s_lshl_b64 s[6:7], s[6:7], 2
	s_mul_hi_i32 s9, s4, 0x1800000
	s_add_u32 s8, s8, s6
	s_addc_u32 s9, s9, s7
	v_mov_b32_e32 v8, 0
	v_lshl_add_u64 v[6:7], v[4:5], 0, s[8:9]
	v_readlane_b32 s20, v254, 55
	v_readlane_b32 s21, v254, 56
	s_add_u32 s20, s20, s8
	s_addc_u32 s21, s21, s9
	s_mov_b64 s[8:9], 0
	v_mov_b32_e32 v19, v16
	v_mov_b32_e32 v9, v8
	v_mov_b32_e32 v10, v8
	v_mov_b32_e32 v11, v8
	v_mov_b32_e32 v12, v8
	v_mov_b32_e32 v13, v8
	v_mov_b32_e32 v14, v8
	v_mov_b32_e32 v15, v8
	v_mov_b32_e32 v20, v8
	s_mov_b32 s8, 0
	global_load_dword v80, v74, s[20:21]
	s_add_u32 s20, s20, 0x6000
	s_addc_u32 s21, s21, 0
	global_load_dword v82, v74, s[20:21]
	s_add_u32 s20, s20, 0x6000
	s_addc_u32 s21, s21, 0
	global_load_dword v84, v74, s[20:21]
	s_add_u32 s20, s20, 0x6000
	s_addc_u32 s21, s21, 0
	global_load_dword v86, v74, s[20:21]
	s_add_u32 s20, s20, 0x6000
	s_addc_u32 s21, s21, 0
	global_load_dword v88, v74, s[20:21]
	s_add_u32 s20, s20, 0x6000
	s_addc_u32 s21, s21, 0
	global_load_dword v90, v74, s[20:21]
	s_add_u32 s20, s20, 0x6000
	s_addc_u32 s21, s21, 0
	global_load_dword v92, v74, s[20:21]
	s_add_u32 s20, s20, 0x6000
	s_addc_u32 s21, s21, 0
	global_load_dword v94, v74, s[20:21]
	s_add_u32 s20, s20, 0x6000
	s_addc_u32 s21, s21, 0
	global_load_dword v96, v74, s[20:21]
	s_add_u32 s20, s20, 0x6000
	s_addc_u32 s21, s21, 0
	global_load_dword v98, v74, s[20:21]
	s_add_u32 s20, s20, 0x6000
	s_addc_u32 s21, s21, 0
	global_load_dword v100, v74, s[20:21]
	s_add_u32 s20, s20, 0x6000
	s_addc_u32 s21, s21, 0
	global_load_dword v102, v74, s[20:21]
	s_add_u32 s20, s20, 0x6000
	s_addc_u32 s21, s21, 0
	global_load_dword v104, v74, s[20:21]
	s_add_u32 s20, s20, 0x6000
	s_addc_u32 s21, s21, 0
	global_load_dword v106, v74, s[20:21]
	s_add_u32 s20, s20, 0x6000
	s_addc_u32 s21, s21, 0
	global_load_dword v108, v74, s[20:21]
	s_add_u32 s20, s20, 0x6000
	s_addc_u32 s21, s21, 0
	global_load_dword v110, v74, s[20:21]
	s_add_u32 s20, s20, 0x6000
	s_addc_u32 s21, s21, 0
.LBB0_855:
	global_load_dword v112, v74, s[20:21]
	s_add_u32 s20, s20, 0x6000
	s_addc_u32 s21, s21, 0
	global_load_dword v114, v74, s[20:21]
	s_add_u32 s20, s20, 0x6000
	s_addc_u32 s21, s21, 0
	global_load_dword v116, v74, s[20:21]
	s_add_u32 s20, s20, 0x6000
	s_addc_u32 s21, s21, 0
	global_load_dword v118, v74, s[20:21]
	s_add_u32 s20, s20, 0x6000
	s_addc_u32 s21, s21, 0
	global_load_dword v120, v74, s[20:21]
	s_add_u32 s20, s20, 0x6000
	s_addc_u32 s21, s21, 0
	global_load_dword v122, v74, s[20:21]
	s_add_u32 s20, s20, 0x6000
	s_addc_u32 s21, s21, 0
	global_load_dword v124, v74, s[20:21]
	s_add_u32 s20, s20, 0x6000
	s_addc_u32 s21, s21, 0
	global_load_dword v126, v74, s[20:21]
	s_add_u32 s20, s20, 0x6000
	s_addc_u32 s21, s21, 0
	global_load_dword v128, v74, s[20:21]
	s_add_u32 s20, s20, 0x6000
	s_addc_u32 s21, s21, 0
	global_load_dword v130, v74, s[20:21]
	s_add_u32 s20, s20, 0x6000
	s_addc_u32 s21, s21, 0
	global_load_dword v132, v74, s[20:21]
	s_add_u32 s20, s20, 0x6000
	s_addc_u32 s21, s21, 0
	global_load_dword v134, v74, s[20:21]
	s_add_u32 s20, s20, 0x6000
	s_addc_u32 s21, s21, 0
	global_load_dword v136, v74, s[20:21]
	s_add_u32 s20, s20, 0x6000
	s_addc_u32 s21, s21, 0
	global_load_dword v138, v74, s[20:21]
	s_add_u32 s20, s20, 0x6000
	s_addc_u32 s21, s21, 0
	global_load_dword v140, v74, s[20:21]
	s_add_u32 s20, s20, 0x6000
	s_addc_u32 s21, s21, 0
	global_load_dword v142, v74, s[20:21]
	s_add_u32 s20, s20, 0x6000
	s_addc_u32 s21, s21, 0
	ds_read_b128 v[22:25], v19 offset:4096
	ds_read_b128 v[26:29], v19 offset:8192
	ds_read_b128 v[30:33], v19 offset:12288
	ds_read_b128 v[34:37], v19 offset:16384
	ds_read_b128 v[38:41], v19 offset:20480
	ds_read_b128 v[42:45], v19 offset:24576
	ds_read_b128 v[46:49], v19 offset:28672
	ds_read_b128 v[50:53], v19 offset:0
	ds_read_b128 v[54:57], v19 offset:32768
	s_waitcnt lgkmcnt(8)
	v_mov_b32_e32 v67, v22
	s_waitcnt lgkmcnt(7)
	v_mov_b32_e32 v68, v26
	s_waitcnt lgkmcnt(6)
	v_mov_b32_e32 v69, v30
	s_waitcnt lgkmcnt(1)
	v_mov_b32_e32 v66, v50
	v_mov_b32_e32 v70, v34
	v_mov_b32_e32 v71, v38
	v_mov_b32_e32 v72, v42
	v_mov_b32_e32 v73, v46
	v_mov_b32_e32 v22, v51
	v_mov_b32_e32 v30, v27
	v_mov_b32_e32 v38, v35
	v_mov_b32_e32 v46, v43
	v_mov_b32_e32 v26, v52
	v_mov_b32_e32 v27, v24
	v_mov_b32_e32 v34, v28
	v_mov_b32_e32 v35, v32
	v_mov_b32_e32 v42, v36
	v_mov_b32_e32 v43, v40
	v_mov_b32_e32 v50, v44
	v_mov_b32_e32 v51, v48
	v_mov_b32_e32 v24, v53
	v_mov_b32_e32 v32, v29
	v_mov_b32_e32 v40, v37
	v_mov_b32_e32 v48, v45
	s_waitcnt vmcnt(31)
	v_pk_fma_f32 v[8:9], v[66:67], v[80:81], v[8:9] op_sel_hi:[1,0,1]
	v_pk_fma_f32 v[10:11], v[68:69], v[80:81], v[10:11] op_sel_hi:[1,0,1]
	v_pk_fma_f32 v[12:13], v[70:71], v[80:81], v[12:13] op_sel_hi:[1,0,1]
	v_pk_fma_f32 v[14:15], v[72:73], v[80:81], v[14:15] op_sel_hi:[1,0,1]
	s_waitcnt lgkmcnt(0)
	v_fmac_f32_e32 v20, v54, v80
	s_waitcnt vmcnt(30)
	v_pk_fma_f32 v[8:9], v[22:23], v[82:83], v[8:9] op_sel_hi:[1,0,1]
	v_pk_fma_f32 v[10:11], v[30:31], v[82:83], v[10:11] op_sel_hi:[1,0,1]
	v_pk_fma_f32 v[12:13], v[38:39], v[82:83], v[12:13] op_sel_hi:[1,0,1]
	v_pk_fma_f32 v[14:15], v[46:47], v[82:83], v[14:15] op_sel_hi:[1,0,1]
	v_fmac_f32_e32 v20, v55, v82
	s_waitcnt vmcnt(29)
	v_pk_fma_f32 v[8:9], v[26:27], v[84:85], v[8:9] op_sel_hi:[1,0,1]
	v_pk_fma_f32 v[10:11], v[34:35], v[84:85], v[10:11] op_sel_hi:[1,0,1]
	v_pk_fma_f32 v[12:13], v[42:43], v[84:85], v[12:13] op_sel_hi:[1,0,1]
	v_pk_fma_f32 v[14:15], v[50:51], v[84:85], v[14:15] op_sel_hi:[1,0,1]
	v_fmac_f32_e32 v20, v56, v84
	s_waitcnt vmcnt(28)
; __device__ __forceinline__ void mod_phase(const Params& p, char* smem, int tid, int bid) {
;     ...
; #pragma unroll 4
;     for (int k = kg * 256; k < kg * 256 + 256; ++k) {
;       const float w = W[(size_t)k * 6144];
; #pragma unroll
;       for (int r = 0; r < 9; ++r) acc[r] = fmaf(sL[r * 1024 + k], w, acc[r]);
	v_pk_fma_f32 v[8:9], v[24:25], v[86:87], v[8:9] op_sel_hi:[1,0,1]
	v_pk_fma_f32 v[10:11], v[32:33], v[86:87], v[10:11] op_sel_hi:[1,0,1]
	v_pk_fma_f32 v[12:13], v[40:41], v[86:87], v[12:13] op_sel_hi:[1,0,1]
	v_pk_fma_f32 v[14:15], v[48:49], v[86:87], v[14:15] op_sel_hi:[1,0,1]
	v_fmac_f32_e32 v20, v57, v86
	ds_read_b128 v[22:25], v19 offset:4112
	ds_read_b128 v[26:29], v19 offset:8208
	ds_read_b128 v[30:33], v19 offset:12304
	ds_read_b128 v[34:37], v19 offset:16400
	ds_read_b128 v[38:41], v19 offset:20496
	ds_read_b128 v[42:45], v19 offset:24592
	ds_read_b128 v[46:49], v19 offset:28688
	ds_read_b128 v[50:53], v19 offset:16
	ds_read_b128 v[54:57], v19 offset:32784
	s_waitcnt lgkmcnt(8)
	v_mov_b32_e32 v67, v22
	s_waitcnt lgkmcnt(7)
	v_mov_b32_e32 v68, v26
	s_waitcnt lgkmcnt(6)
	v_mov_b32_e32 v69, v30
	s_waitcnt lgkmcnt(1)
	v_mov_b32_e32 v66, v50
	v_mov_b32_e32 v70, v34
	v_mov_b32_e32 v71, v38
	v_mov_b32_e32 v72, v42
	v_mov_b32_e32 v73, v46
	v_mov_b32_e32 v22, v51
	v_mov_b32_e32 v30, v27
	v_mov_b32_e32 v38, v35
	v_mov_b32_e32 v46, v43
	v_mov_b32_e32 v26, v52
	v_mov_b32_e32 v27, v24
	v_mov_b32_e32 v34, v28
	v_mov_b32_e32 v35, v32
	v_mov_b32_e32 v42, v36
	v_mov_b32_e32 v43, v40
	v_mov_b32_e32 v50, v44
	v_mov_b32_e32 v51, v48
	v_mov_b32_e32 v24, v53
	v_mov_b32_e32 v32, v29
	v_mov_b32_e32 v40, v37
	v_mov_b32_e32 v48, v45
	s_waitcnt vmcnt(27)
	v_pk_fma_f32 v[8:9], v[66:67], v[88:89], v[8:9] op_sel_hi:[1,0,1]
	v_pk_fma_f32 v[10:11], v[68:69], v[88:89], v[10:11] op_sel_hi:[1,0,1]
	v_pk_fma_f32 v[12:13], v[70:71], v[88:89], v[12:13] op_sel_hi:[1,0,1]
	v_pk_fma_f32 v[14:15], v[72:73], v[88:89], v[14:15] op_sel_hi:[1,0,1]
	s_waitcnt lgkmcnt(0)
	v_fmac_f32_e32 v20, v54, v88
	s_waitcnt vmcnt(26)
	v_pk_fma_f32 v[8:9], v[22:23], v[90:91], v[8:9] op_sel_hi:[1,0,1]
	v_pk_fma_f32 v[10:11], v[30:31], v[90:91], v[10:11] op_sel_hi:[1,0,1]
	v_pk_fma_f32 v[12:13], v[38:39], v[90:91], v[12:13] op_sel_hi:[1,0,1]
	v_pk_fma_f32 v[14:15], v[46:47], v[90:91], v[14:15] op_sel_hi:[1,0,1]
	v_fmac_f32_e32 v20, v55, v90
	s_waitcnt vmcnt(25)
	v_pk_fma_f32 v[8:9], v[26:27], v[92:93], v[8:9] op_sel_hi:[1,0,1]
	v_pk_fma_f32 v[10:11], v[34:35], v[92:93], v[10:11] op_sel_hi:[1,0,1]
	v_pk_fma_f32 v[12:13], v[42:43], v[92:93], v[12:13] op_sel_hi:[1,0,1]
	v_pk_fma_f32 v[14:15], v[50:51], v[92:93], v[14:15] op_sel_hi:[1,0,1]
	v_fmac_f32_e32 v20, v56, v92
	s_waitcnt vmcnt(24)
	v_pk_fma_f32 v[8:9], v[24:25], v[94:95], v[8:9] op_sel_hi:[1,0,1]
	v_pk_fma_f32 v[10:11], v[32:33], v[94:95], v[10:11] op_sel_hi:[1,0,1]
	v_pk_fma_f32 v[12:13], v[40:41], v[94:95], v[12:13] op_sel_hi:[1,0,1]
	v_pk_fma_f32 v[14:15], v[48:49], v[94:95], v[14:15] op_sel_hi:[1,0,1]
	v_fmac_f32_e32 v20, v57, v94
	ds_read_b128 v[22:25], v19 offset:4128
	ds_read_b128 v[26:29], v19 offset:8224
	ds_read_b128 v[30:33], v19 offset:12320
	ds_read_b128 v[34:37], v19 offset:16416
	ds_read_b128 v[38:41], v19 offset:20512
	ds_read_b128 v[42:45], v19 offset:24608
	ds_read_b128 v[46:49], v19 offset:28704
	ds_read_b128 v[50:53], v19 offset:32
	ds_read_b128 v[54:57], v19 offset:32800
	s_waitcnt lgkmcnt(8)
	v_mov_b32_e32 v67, v22
	s_waitcnt lgkmcnt(7)
	v_mov_b32_e32 v68, v26
	s_waitcnt lgkmcnt(6)
	v_mov_b32_e32 v69, v30
	s_waitcnt lgkmcnt(1)
	v_mov_b32_e32 v66, v50
	v_mov_b32_e32 v70, v34
	v_mov_b32_e32 v71, v38
	v_mov_b32_e32 v72, v42
	v_mov_b32_e32 v73, v46
	v_mov_b32_e32 v22, v51
	v_mov_b32_e32 v30, v27
	v_mov_b32_e32 v38, v35
	v_mov_b32_e32 v46, v43
	v_mov_b32_e32 v26, v52
	v_mov_b32_e32 v27, v24
	v_mov_b32_e32 v34, v28
	v_mov_b32_e32 v35, v32
	v_mov_b32_e32 v42, v36
	v_mov_b32_e32 v43, v40
	v_mov_b32_e32 v50, v44
	v_mov_b32_e32 v51, v48
	v_mov_b32_e32 v24, v53
	v_mov_b32_e32 v32, v29
	v_mov_b32_e32 v40, v37
	v_mov_b32_e32 v48, v45
	s_waitcnt vmcnt(23)
	v_pk_fma_f32 v[8:9], v[66:67], v[96:97], v[8:9] op_sel_hi:[1,0,1]
	v_pk_fma_f32 v[10:11], v[68:69], v[96:97], v[10:11] op_sel_hi:[1,0,1]
	v_pk_fma_f32 v[12:13], v[70:71], v[96:97], v[12:13] op_sel_hi:[1,0,1]
	v_pk_fma_f32 v[14:15], v[72:73], v[96:97], v[14:15] op_sel_hi:[1,0,1]
	s_waitcnt lgkmcnt(0)
	v_fmac_f32_e32 v20, v54, v96
	s_waitcnt vmcnt(22)
	v_pk_fma_f32 v[8:9], v[22:23], v[98:99], v[8:9] op_sel_hi:[1,0,1]
	v_pk_fma_f32 v[10:11], v[30:31], v[98:99], v[10:11] op_sel_hi:[1,0,1]
	v_pk_fma_f32 v[12:13], v[38:39], v[98:99], v[12:13] op_sel_hi:[1,0,1]
	v_pk_fma_f32 v[14:15], v[46:47], v[98:99], v[14:15] op_sel_hi:[1,0,1]
	v_fmac_f32_e32 v20, v55, v98
	s_waitcnt vmcnt(21)
	v_pk_fma_f32 v[8:9], v[26:27], v[100:101], v[8:9] op_sel_hi:[1,0,1]
	v_pk_fma_f32 v[10:11], v[34:35], v[100:101], v[10:11] op_sel_hi:[1,0,1]
	v_pk_fma_f32 v[12:13], v[42:43], v[100:101], v[12:13] op_sel_hi:[1,0,1]
	v_pk_fma_f32 v[14:15], v[50:51], v[100:101], v[14:15] op_sel_hi:[1,0,1]
	v_fmac_f32_e32 v20, v56, v100
	s_waitcnt vmcnt(20)
	v_pk_fma_f32 v[8:9], v[24:25], v[102:103], v[8:9] op_sel_hi:[1,0,1]
	v_pk_fma_f32 v[10:11], v[32:33], v[102:103], v[10:11] op_sel_hi:[1,0,1]
	v_pk_fma_f32 v[12:13], v[40:41], v[102:103], v[12:13] op_sel_hi:[1,0,1]
	v_pk_fma_f32 v[14:15], v[48:49], v[102:103], v[14:15] op_sel_hi:[1,0,1]
	v_fmac_f32_e32 v20, v57, v102
	ds_read_b128 v[22:25], v19 offset:4144
	ds_read_b128 v[26:29], v19 offset:8240
	ds_read_b128 v[30:33], v19 offset:12336
	ds_read_b128 v[34:37], v19 offset:16432
	ds_read_b128 v[38:41], v19 offset:20528
	ds_read_b128 v[42:45], v19 offset:24624
	ds_read_b128 v[46:49], v19 offset:28720
	ds_read_b128 v[50:53], v19 offset:48
	ds_read_b128 v[54:57], v19 offset:32816
	s_waitcnt lgkmcnt(8)
	v_mov_b32_e32 v67, v22
	s_waitcnt lgkmcnt(7)
	v_mov_b32_e32 v68, v26
	s_waitcnt lgkmcnt(6)
	v_mov_b32_e32 v69, v30
	s_waitcnt lgkmcnt(1)
; __device__ __forceinline__ void mod_phase(const Params& p, char* smem, int tid, int bid) {
;     ...
; #pragma unroll 4
;     for (int k = kg * 256; k < kg * 256 + 256; ++k) {
;       const float w = W[(size_t)k * 6144];
; #pragma unroll
;       for (int r = 0; r < 9; ++r) acc[r] = fmaf(sL[r * 1024 + k], w, acc[r]);
	v_mov_b32_e32 v66, v50
	v_mov_b32_e32 v70, v34
	v_mov_b32_e32 v71, v38
	v_mov_b32_e32 v72, v42
	v_mov_b32_e32 v73, v46
	v_mov_b32_e32 v22, v51
	v_mov_b32_e32 v30, v27
	v_mov_b32_e32 v38, v35
	v_mov_b32_e32 v46, v43
	v_mov_b32_e32 v26, v52
	v_mov_b32_e32 v27, v24
	v_mov_b32_e32 v34, v28
	v_mov_b32_e32 v35, v32
	v_mov_b32_e32 v42, v36
	v_mov_b32_e32 v43, v40
	v_mov_b32_e32 v50, v44
	v_mov_b32_e32 v51, v48
	v_mov_b32_e32 v24, v53
	v_mov_b32_e32 v32, v29
	v_mov_b32_e32 v40, v37
	v_mov_b32_e32 v48, v45
	s_waitcnt vmcnt(19)
	v_pk_fma_f32 v[8:9], v[66:67], v[104:105], v[8:9] op_sel_hi:[1,0,1]
	v_pk_fma_f32 v[10:11], v[68:69], v[104:105], v[10:11] op_sel_hi:[1,0,1]
	v_pk_fma_f32 v[12:13], v[70:71], v[104:105], v[12:13] op_sel_hi:[1,0,1]
	v_pk_fma_f32 v[14:15], v[72:73], v[104:105], v[14:15] op_sel_hi:[1,0,1]
	s_waitcnt lgkmcnt(0)
	v_fmac_f32_e32 v20, v54, v104
	s_waitcnt vmcnt(18)
	v_pk_fma_f32 v[8:9], v[22:23], v[106:107], v[8:9] op_sel_hi:[1,0,1]
	v_pk_fma_f32 v[10:11], v[30:31], v[106:107], v[10:11] op_sel_hi:[1,0,1]
	v_pk_fma_f32 v[12:13], v[38:39], v[106:107], v[12:13] op_sel_hi:[1,0,1]
	v_pk_fma_f32 v[14:15], v[46:47], v[106:107], v[14:15] op_sel_hi:[1,0,1]
	v_fmac_f32_e32 v20, v55, v106
	s_waitcnt vmcnt(17)
	v_pk_fma_f32 v[8:9], v[26:27], v[108:109], v[8:9] op_sel_hi:[1,0,1]
	v_pk_fma_f32 v[10:11], v[34:35], v[108:109], v[10:11] op_sel_hi:[1,0,1]
	v_pk_fma_f32 v[12:13], v[42:43], v[108:109], v[12:13] op_sel_hi:[1,0,1]
	v_pk_fma_f32 v[14:15], v[50:51], v[108:109], v[14:15] op_sel_hi:[1,0,1]
	v_fmac_f32_e32 v20, v56, v108
	s_waitcnt vmcnt(16)
	v_pk_fma_f32 v[8:9], v[24:25], v[110:111], v[8:9] op_sel_hi:[1,0,1]
	v_pk_fma_f32 v[10:11], v[32:33], v[110:111], v[10:11] op_sel_hi:[1,0,1]
	v_pk_fma_f32 v[12:13], v[40:41], v[110:111], v[12:13] op_sel_hi:[1,0,1]
	v_pk_fma_f32 v[14:15], v[48:49], v[110:111], v[14:15] op_sel_hi:[1,0,1]
	v_fmac_f32_e32 v20, v57, v110
	v_add_u32_e32 v19, 64, v19
	s_cmp_eq_u32 s8, 7
	s_cselect_b32 s11, 0x60000, 0
	s_sub_u32 s20, s20, s11
	s_subb_u32 s21, s21, 0
	global_load_dword v80, v74, s[20:21]
	s_add_u32 s20, s20, 0x6000
	s_addc_u32 s21, s21, 0
	global_load_dword v82, v74, s[20:21]
	s_add_u32 s20, s20, 0x6000
	s_addc_u32 s21, s21, 0
	global_load_dword v84, v74, s[20:21]
	s_add_u32 s20, s20, 0x6000
	s_addc_u32 s21, s21, 0
	global_load_dword v86, v74, s[20:21]
	s_add_u32 s20, s20, 0x6000
	s_addc_u32 s21, s21, 0
	global_load_dword v88, v74, s[20:21]
	s_add_u32 s20, s20, 0x6000
	s_addc_u32 s21, s21, 0
	global_load_dword v90, v74, s[20:21]
	s_add_u32 s20, s20, 0x6000
	s_addc_u32 s21, s21, 0
	global_load_dword v92, v74, s[20:21]
	s_add_u32 s20, s20, 0x6000
	s_addc_u32 s21, s21, 0
	global_load_dword v94, v74, s[20:21]
	s_add_u32 s20, s20, 0x6000
	s_addc_u32 s21, s21, 0
	global_load_dword v96, v74, s[20:21]
	s_add_u32 s20, s20, 0x6000
	s_addc_u32 s21, s21, 0
	global_load_dword v98, v74, s[20:21]
	s_add_u32 s20, s20, 0x6000
	s_addc_u32 s21, s21, 0
	global_load_dword v100, v74, s[20:21]
	s_add_u32 s20, s20, 0x6000
	s_addc_u32 s21, s21, 0
	global_load_dword v102, v74, s[20:21]
	s_add_u32 s20, s20, 0x6000
	s_addc_u32 s21, s21, 0
	global_load_dword v104, v74, s[20:21]
	s_add_u32 s20, s20, 0x6000
	s_addc_u32 s21, s21, 0
	global_load_dword v106, v74, s[20:21]
	s_add_u32 s20, s20, 0x6000
	s_addc_u32 s21, s21, 0
	global_load_dword v108, v74, s[20:21]
	s_add_u32 s20, s20, 0x6000
	s_addc_u32 s21, s21, 0
	global_load_dword v110, v74, s[20:21]
	s_add_u32 s20, s20, 0x6000
	s_addc_u32 s21, s21, 0
	ds_read_b128 v[22:25], v19 offset:4096
	ds_read_b128 v[26:29], v19 offset:8192
	ds_read_b128 v[30:33], v19 offset:12288
	ds_read_b128 v[34:37], v19 offset:16384
	ds_read_b128 v[38:41], v19 offset:20480
	ds_read_b128 v[42:45], v19 offset:24576
	ds_read_b128 v[46:49], v19 offset:28672
	ds_read_b128 v[50:53], v19 offset:0
	ds_read_b128 v[54:57], v19 offset:32768
	s_waitcnt lgkmcnt(8)
	v_mov_b32_e32 v67, v22
	s_waitcnt lgkmcnt(7)
	v_mov_b32_e32 v68, v26
	s_waitcnt lgkmcnt(6)
	v_mov_b32_e32 v69, v30
	s_waitcnt lgkmcnt(1)
	v_mov_b32_e32 v66, v50
	v_mov_b32_e32 v70, v34
	v_mov_b32_e32 v71, v38
	v_mov_b32_e32 v72, v42
	v_mov_b32_e32 v73, v46
	v_mov_b32_e32 v22, v51
	v_mov_b32_e32 v30, v27
	v_mov_b32_e32 v38, v35
	v_mov_b32_e32 v46, v43
	v_mov_b32_e32 v26, v52
	v_mov_b32_e32 v27, v24
	v_mov_b32_e32 v34, v28
	v_mov_b32_e32 v35, v32
	v_mov_b32_e32 v42, v36
	v_mov_b32_e32 v43, v40
	v_mov_b32_e32 v50, v44
	v_mov_b32_e32 v51, v48
	v_mov_b32_e32 v24, v53
	v_mov_b32_e32 v32, v29
	v_mov_b32_e32 v40, v37
	v_mov_b32_e32 v48, v45
	s_waitcnt vmcnt(31)
	v_pk_fma_f32 v[8:9], v[66:67], v[112:113], v[8:9] op_sel_hi:[1,0,1]
	v_pk_fma_f32 v[10:11], v[68:69], v[112:113], v[10:11] op_sel_hi:[1,0,1]
	v_pk_fma_f32 v[12:13], v[70:71], v[112:113], v[12:13] op_sel_hi:[1,0,1]
	v_pk_fma_f32 v[14:15], v[72:73], v[112:113], v[14:15] op_sel_hi:[1,0,1]
	s_waitcnt lgkmcnt(0)
	v_fmac_f32_e32 v20, v54, v112
	s_waitcnt vmcnt(30)
	v_pk_fma_f32 v[8:9], v[22:23], v[114:115], v[8:9] op_sel_hi:[1,0,1]
	v_pk_fma_f32 v[10:11], v[30:31], v[114:115], v[10:11] op_sel_hi:[1,0,1]
	v_pk_fma_f32 v[12:13], v[38:39], v[114:115], v[12:13] op_sel_hi:[1,0,1]
	v_pk_fma_f32 v[14:15], v[46:47], v[114:115], v[14:15] op_sel_hi:[1,0,1]
	v_fmac_f32_e32 v20, v55, v114
	s_waitcnt vmcnt(29)
	v_pk_fma_f32 v[8:9], v[26:27], v[116:117], v[8:9] op_sel_hi:[1,0,1]
	v_pk_fma_f32 v[10:11], v[34:35], v[116:117], v[10:11] op_sel_hi:[1,0,1]
	v_pk_fma_f32 v[12:13], v[42:43], v[116:117], v[12:13] op_sel_hi:[1,0,1]
	v_pk_fma_f32 v[14:15], v[50:51], v[116:117], v[14:15] op_sel_hi:[1,0,1]
	v_fmac_f32_e32 v20, v56, v116
	s_waitcnt vmcnt(28)
; __device__ __forceinline__ void mod_phase(const Params& p, char* smem, int tid, int bid) {
;     ...
; #pragma unroll 4
;     for (int k = kg * 256; k < kg * 256 + 256; ++k) {
;       const float w = W[(size_t)k * 6144];
; #pragma unroll
;       for (int r = 0; r < 9; ++r) acc[r] = fmaf(sL[r * 1024 + k], w, acc[r]);
	v_pk_fma_f32 v[8:9], v[24:25], v[118:119], v[8:9] op_sel_hi:[1,0,1]
	v_pk_fma_f32 v[10:11], v[32:33], v[118:119], v[10:11] op_sel_hi:[1,0,1]
	v_pk_fma_f32 v[12:13], v[40:41], v[118:119], v[12:13] op_sel_hi:[1,0,1]
	v_pk_fma_f32 v[14:15], v[48:49], v[118:119], v[14:15] op_sel_hi:[1,0,1]
	v_fmac_f32_e32 v20, v57, v118
	ds_read_b128 v[22:25], v19 offset:4112
	ds_read_b128 v[26:29], v19 offset:8208
	ds_read_b128 v[30:33], v19 offset:12304
	ds_read_b128 v[34:37], v19 offset:16400
	ds_read_b128 v[38:41], v19 offset:20496
	ds_read_b128 v[42:45], v19 offset:24592
	ds_read_b128 v[46:49], v19 offset:28688
	ds_read_b128 v[50:53], v19 offset:16
	ds_read_b128 v[54:57], v19 offset:32784
	s_waitcnt lgkmcnt(8)
	v_mov_b32_e32 v67, v22
	s_waitcnt lgkmcnt(7)
	v_mov_b32_e32 v68, v26
	s_waitcnt lgkmcnt(6)
	v_mov_b32_e32 v69, v30
	s_waitcnt lgkmcnt(1)
	v_mov_b32_e32 v66, v50
	v_mov_b32_e32 v70, v34
	v_mov_b32_e32 v71, v38
	v_mov_b32_e32 v72, v42
	v_mov_b32_e32 v73, v46
	v_mov_b32_e32 v22, v51
	v_mov_b32_e32 v30, v27
	v_mov_b32_e32 v38, v35
	v_mov_b32_e32 v46, v43
	v_mov_b32_e32 v26, v52
	v_mov_b32_e32 v27, v24
	v_mov_b32_e32 v34, v28
	v_mov_b32_e32 v35, v32
	v_mov_b32_e32 v42, v36
	v_mov_b32_e32 v43, v40
	v_mov_b32_e32 v50, v44
	v_mov_b32_e32 v51, v48
	v_mov_b32_e32 v24, v53
	v_mov_b32_e32 v32, v29
	v_mov_b32_e32 v40, v37
	v_mov_b32_e32 v48, v45
	s_waitcnt vmcnt(27)
	v_pk_fma_f32 v[8:9], v[66:67], v[120:121], v[8:9] op_sel_hi:[1,0,1]
	v_pk_fma_f32 v[10:11], v[68:69], v[120:121], v[10:11] op_sel_hi:[1,0,1]
	v_pk_fma_f32 v[12:13], v[70:71], v[120:121], v[12:13] op_sel_hi:[1,0,1]
	v_pk_fma_f32 v[14:15], v[72:73], v[120:121], v[14:15] op_sel_hi:[1,0,1]
	s_waitcnt lgkmcnt(0)
	v_fmac_f32_e32 v20, v54, v120
	s_waitcnt vmcnt(26)
	v_pk_fma_f32 v[8:9], v[22:23], v[122:123], v[8:9] op_sel_hi:[1,0,1]
	v_pk_fma_f32 v[10:11], v[30:31], v[122:123], v[10:11] op_sel_hi:[1,0,1]
	v_pk_fma_f32 v[12:13], v[38:39], v[122:123], v[12:13] op_sel_hi:[1,0,1]
	v_pk_fma_f32 v[14:15], v[46:47], v[122:123], v[14:15] op_sel_hi:[1,0,1]
	v_fmac_f32_e32 v20, v55, v122
	s_waitcnt vmcnt(25)
	v_pk_fma_f32 v[8:9], v[26:27], v[124:125], v[8:9] op_sel_hi:[1,0,1]
	v_pk_fma_f32 v[10:11], v[34:35], v[124:125], v[10:11] op_sel_hi:[1,0,1]
	v_pk_fma_f32 v[12:13], v[42:43], v[124:125], v[12:13] op_sel_hi:[1,0,1]
	v_pk_fma_f32 v[14:15], v[50:51], v[124:125], v[14:15] op_sel_hi:[1,0,1]
	v_fmac_f32_e32 v20, v56, v124
	s_waitcnt vmcnt(24)
	v_pk_fma_f32 v[8:9], v[24:25], v[126:127], v[8:9] op_sel_hi:[1,0,1]
	v_pk_fma_f32 v[10:11], v[32:33], v[126:127], v[10:11] op_sel_hi:[1,0,1]
	v_pk_fma_f32 v[12:13], v[40:41], v[126:127], v[12:13] op_sel_hi:[1,0,1]
	v_pk_fma_f32 v[14:15], v[48:49], v[126:127], v[14:15] op_sel_hi:[1,0,1]
	v_fmac_f32_e32 v20, v57, v126
	ds_read_b128 v[22:25], v19 offset:4128
	ds_read_b128 v[26:29], v19 offset:8224
	ds_read_b128 v[30:33], v19 offset:12320
	ds_read_b128 v[34:37], v19 offset:16416
	ds_read_b128 v[38:41], v19 offset:20512
	ds_read_b128 v[42:45], v19 offset:24608
	ds_read_b128 v[46:49], v19 offset:28704
	ds_read_b128 v[50:53], v19 offset:32
	ds_read_b128 v[54:57], v19 offset:32800
	s_waitcnt lgkmcnt(8)
	v_mov_b32_e32 v67, v22
	s_waitcnt lgkmcnt(7)
	v_mov_b32_e32 v68, v26
	s_waitcnt lgkmcnt(6)
	v_mov_b32_e32 v69, v30
	s_waitcnt lgkmcnt(1)
	v_mov_b32_e32 v66, v50
	v_mov_b32_e32 v70, v34
	v_mov_b32_e32 v71, v38
	v_mov_b32_e32 v72, v42
	v_mov_b32_e32 v73, v46
	v_mov_b32_e32 v22, v51
	v_mov_b32_e32 v30, v27
	v_mov_b32_e32 v38, v35
	v_mov_b32_e32 v46, v43
	v_mov_b32_e32 v26, v52
	v_mov_b32_e32 v27, v24
	v_mov_b32_e32 v34, v28
	v_mov_b32_e32 v35, v32
	v_mov_b32_e32 v42, v36
	v_mov_b32_e32 v43, v40
	v_mov_b32_e32 v50, v44
	v_mov_b32_e32 v51, v48
	v_mov_b32_e32 v24, v53
	v_mov_b32_e32 v32, v29
	v_mov_b32_e32 v40, v37
	v_mov_b32_e32 v48, v45
	s_waitcnt vmcnt(23)
	v_pk_fma_f32 v[8:9], v[66:67], v[128:129], v[8:9] op_sel_hi:[1,0,1]
	v_pk_fma_f32 v[10:11], v[68:69], v[128:129], v[10:11] op_sel_hi:[1,0,1]
	v_pk_fma_f32 v[12:13], v[70:71], v[128:129], v[12:13] op_sel_hi:[1,0,1]
	v_pk_fma_f32 v[14:15], v[72:73], v[128:129], v[14:15] op_sel_hi:[1,0,1]
	s_waitcnt lgkmcnt(0)
	v_fmac_f32_e32 v20, v54, v128
	s_waitcnt vmcnt(22)
	v_pk_fma_f32 v[8:9], v[22:23], v[130:131], v[8:9] op_sel_hi:[1,0,1]
	v_pk_fma_f32 v[10:11], v[30:31], v[130:131], v[10:11] op_sel_hi:[1,0,1]
	v_pk_fma_f32 v[12:13], v[38:39], v[130:131], v[12:13] op_sel_hi:[1,0,1]
	v_pk_fma_f32 v[14:15], v[46:47], v[130:131], v[14:15] op_sel_hi:[1,0,1]
	v_fmac_f32_e32 v20, v55, v130
	s_waitcnt vmcnt(21)
	v_pk_fma_f32 v[8:9], v[26:27], v[132:133], v[8:9] op_sel_hi:[1,0,1]
	v_pk_fma_f32 v[10:11], v[34:35], v[132:133], v[10:11] op_sel_hi:[1,0,1]
	v_pk_fma_f32 v[12:13], v[42:43], v[132:133], v[12:13] op_sel_hi:[1,0,1]
	v_pk_fma_f32 v[14:15], v[50:51], v[132:133], v[14:15] op_sel_hi:[1,0,1]
	v_fmac_f32_e32 v20, v56, v132
	s_waitcnt vmcnt(20)
; __device__ __forceinline__ void mod_phase(const Params& p, char* smem, int tid, int bid) {
;     ...
;     for (int k = kg * 256; k < kg * 256 + 256; ++k) {
;       const float w = W[(size_t)k * 6144];
; #pragma unroll
;       for (int r = 0; r < 9; ++r) acc[r] = fmaf(sL[r * 1024 + k], w, acc[r]);
;     }
; #pragma unroll
;     for (int r = 0; r < 9; ++r) red[(kg * 9 + r) * 128 + cl] = acc[r];
;     __syncthreads();
	v_pk_fma_f32 v[8:9], v[24:25], v[134:135], v[8:9] op_sel_hi:[1,0,1]
	v_pk_fma_f32 v[10:11], v[32:33], v[134:135], v[10:11] op_sel_hi:[1,0,1]
	v_pk_fma_f32 v[12:13], v[40:41], v[134:135], v[12:13] op_sel_hi:[1,0,1]
	v_pk_fma_f32 v[14:15], v[48:49], v[134:135], v[14:15] op_sel_hi:[1,0,1]
	v_fmac_f32_e32 v20, v57, v134
	ds_read_b128 v[22:25], v19 offset:4144
	ds_read_b128 v[26:29], v19 offset:8240
	ds_read_b128 v[30:33], v19 offset:12336
	ds_read_b128 v[34:37], v19 offset:16432
	ds_read_b128 v[38:41], v19 offset:20528
	ds_read_b128 v[42:45], v19 offset:24624
	ds_read_b128 v[46:49], v19 offset:28720
	ds_read_b128 v[50:53], v19 offset:48
	ds_read_b128 v[54:57], v19 offset:32816
	s_waitcnt lgkmcnt(8)
	v_mov_b32_e32 v67, v22
	s_waitcnt lgkmcnt(7)
	v_mov_b32_e32 v68, v26
	s_waitcnt lgkmcnt(6)
	v_mov_b32_e32 v69, v30
	s_waitcnt lgkmcnt(1)
	v_mov_b32_e32 v66, v50
	v_mov_b32_e32 v70, v34
	v_mov_b32_e32 v71, v38
	v_mov_b32_e32 v72, v42
	v_mov_b32_e32 v73, v46
	v_mov_b32_e32 v22, v51
	v_mov_b32_e32 v30, v27
	v_mov_b32_e32 v38, v35
	v_mov_b32_e32 v46, v43
	v_mov_b32_e32 v26, v52
	v_mov_b32_e32 v27, v24
	v_mov_b32_e32 v34, v28
	v_mov_b32_e32 v35, v32
	v_mov_b32_e32 v42, v36
	v_mov_b32_e32 v43, v40
	v_mov_b32_e32 v50, v44
	v_mov_b32_e32 v51, v48
	v_mov_b32_e32 v24, v53
	v_mov_b32_e32 v32, v29
	v_mov_b32_e32 v40, v37
	v_mov_b32_e32 v48, v45
	s_waitcnt vmcnt(19)
	v_pk_fma_f32 v[8:9], v[66:67], v[136:137], v[8:9] op_sel_hi:[1,0,1]
	v_pk_fma_f32 v[10:11], v[68:69], v[136:137], v[10:11] op_sel_hi:[1,0,1]
	v_pk_fma_f32 v[12:13], v[70:71], v[136:137], v[12:13] op_sel_hi:[1,0,1]
	v_pk_fma_f32 v[14:15], v[72:73], v[136:137], v[14:15] op_sel_hi:[1,0,1]
	s_waitcnt lgkmcnt(0)
	v_fmac_f32_e32 v20, v54, v136
	s_waitcnt vmcnt(18)
	v_pk_fma_f32 v[8:9], v[22:23], v[138:139], v[8:9] op_sel_hi:[1,0,1]
	v_pk_fma_f32 v[10:11], v[30:31], v[138:139], v[10:11] op_sel_hi:[1,0,1]
	v_pk_fma_f32 v[12:13], v[38:39], v[138:139], v[12:13] op_sel_hi:[1,0,1]
	v_pk_fma_f32 v[14:15], v[46:47], v[138:139], v[14:15] op_sel_hi:[1,0,1]
	v_fmac_f32_e32 v20, v55, v138
	s_waitcnt vmcnt(17)
	v_pk_fma_f32 v[8:9], v[26:27], v[140:141], v[8:9] op_sel_hi:[1,0,1]
	v_pk_fma_f32 v[10:11], v[34:35], v[140:141], v[10:11] op_sel_hi:[1,0,1]
	v_pk_fma_f32 v[12:13], v[42:43], v[140:141], v[12:13] op_sel_hi:[1,0,1]
	v_pk_fma_f32 v[14:15], v[50:51], v[140:141], v[14:15] op_sel_hi:[1,0,1]
	v_fmac_f32_e32 v20, v56, v140
	s_waitcnt vmcnt(16)
	v_pk_fma_f32 v[8:9], v[24:25], v[142:143], v[8:9] op_sel_hi:[1,0,1]
	v_pk_fma_f32 v[10:11], v[32:33], v[142:143], v[10:11] op_sel_hi:[1,0,1]
	v_pk_fma_f32 v[12:13], v[40:41], v[142:143], v[12:13] op_sel_hi:[1,0,1]
	v_pk_fma_f32 v[14:15], v[48:49], v[142:143], v[14:15] op_sel_hi:[1,0,1]
	v_fmac_f32_e32 v20, v57, v142
	v_add_u32_e32 v19, 64, v19
	s_add_u32 s8, s8, 1
	s_cmp_eq_u32 s8, 8
	s_cbranch_scc0 .LBB0_855
	ds_write2st64_b32 v18, v8, v9 offset0:144 offset1:146
	ds_write2st64_b32 v18, v10, v11 offset0:148 offset1:150
	ds_write2st64_b32 v18, v12, v13 offset0:152 offset1:154
	ds_write2st64_b32 v18, v14, v15 offset0:156 offset1:158
	ds_write_b32 v18, v20 offset:40960
	s_waitcnt lgkmcnt(0)
	s_barrier
	s_and_saveexec_b64 s[8:9], s[0:1]
	s_cbranch_execz .LBB0_853
	v_readlane_b32 s36, v254, 43
	s_mul_i32 s16, s4, 0x6000
	v_readlane_b32 s50, v254, 57
	s_mul_hi_i32 s11, s4, 0x6000
	v_readlane_b32 s51, v254, 58
	s_add_u32 s16, s50, s16
	s_addc_u32 s11, s51, s11
	s_add_u32 s20, s16, s6
	s_addc_u32 s21, s11, s7
	s_and_b32 s18, s10, -8
	s_cmp_gt_u32 s10, 31
	s_cselect_b64 s[22:23], -1, 0
	s_and_b64 s[24:25], s[22:23], exec
	s_cselect_b32 s11, 0xffffffe0, -8
	s_mul_i32 s16, s4, 9
	v_cndmask_b32_e64 v6, 0, 1, s[22:23]
	s_add_i32 s19, s11, s10
	s_lshl_b64 s[10:11], s[4:5], 12
	s_lshl_b32 s4, s4, 1
	v_readlane_b32 s44, v254, 51
	v_readlane_b32 s46, v254, 53
	v_or_b32_e32 v6, s4, v6
	s_and_b64 s[4:5], s[22:23], exec
	v_readlane_b32 s45, v254, 52
	v_readlane_b32 s47, v254, 54
	v_lshl_or_b32 v10, s19, 7, v0
	s_cselect_b32 s4, s46, s44
	v_ashrrev_i32_e32 v11, 31, v10
	s_cselect_b32 s5, s47, s45
	s_add_u32 s4, s4, s10
	v_lshlrev_b32_e32 v200, 2, v0
	v_lshlrev_b64 v[12:13], 2, v[10:11]
	s_addc_u32 s5, s5, s11
	v_mul_lo_u32 v14, v6, 9
	v_lshl_add_u64 v[6:7], s[20:21], 0, v[200:201]
	v_lshl_add_u64 v[8:9], v[2:3], 0, s[6:7]
	v_lshl_add_u64 v[10:11], s[84:85], 0, v[12:13]
	v_lshl_add_u64 v[12:13], s[4:5], 0, v[12:13]
	s_mov_b64 s[4:5], 0
	v_mov_b32_e32 v15, v17
	v_mov_b32_e32 v19, v208
	v_readlane_b32 s37, v254, 44
	v_readlane_b32 s38, v254, 45
	v_readlane_b32 s39, v254, 46
	v_readlane_b32 s40, v254, 47
	v_readlane_b32 s41, v254, 48
	v_readlane_b32 s42, v254, 49
	v_readlane_b32 s43, v254, 50
	v_readlane_b32 s48, v254, 55
	v_readlane_b32 s49, v254, 56
	s_branch .LBB0_859
